# ffn1-down weight transposes moved from phase 0 into the idle last round of up GEMM 1
# baseline (speedup 1.0000x reference)
; #define PG8_WAIT_V(n) asm volatile("s_waitcnt vmcnt(" #n ")" ::: "memory")
; #define PG8_BAR __builtin_amdgcn_s_barrier()
; template <class Epi, class Sched, bool ALIGN_EPI = false, bool SP2 = false>
; __device__ __forceinline__ void gemm_phase(PG8_LAS unsigned char* lds, const Gemm g, const Sched& S, const Epi& E) {
;     ...
;     PG8_WAIT_V(0);
;     if constexpr (!ALIGN_EPI) { if (wr == 0) PG8_BAR; }
;     PG8_BAR;
; DI void p0_prologue(const Args& a, LAS unsigned char* lds, int tid, int wave, int lane, bool first) {
;     ...
;     for (int it = gw; it < NITEMS; it += NGW) {
;         int r = it;
;         if (r < 2 * I_UP) { const int which = r >= I_UP; r -= which * I_UP; const int nb = r % (NUP / 32), kb = r / (NUP / 32);
;             p0_transpose_item(a.in[which ? 18 : 12], D, NUP, srccol_up(32 * nb), (bf16_t*)(ws + (which ? WS_WUP2 : WS_WUP1)), 32 * nb, 64 * kb, scr, lane); continue; }
;         r -= 2 * I_UP;
;         if (r < 2 * I_DN) { const int which = r >= I_DN; r -= which * I_DN; const int nb = r % (D / 32), kb = r / (D / 32);
;             p0_transpose_item(a.in[which ? 19 : 13], FF, D, 32 * nb, (bf16_t*)(ws + (which ? WS_WDN2 : WS_WDN1)), 32 * nb, 64 * kb, scr, lane); continue; }
.LBB0_665:
	s_waitcnt vmcnt(0)
	v_readlane_b32 s36, v255, 19
	v_readlane_b32 s28, v255, 33
	v_readlane_b32 s30, v255, 35
	s_barrier
	v_readlane_b32 s65, v255, 50
	v_readlane_b32 s37, v255, 20
	v_readlane_b32 s38, v255, 21
	v_readlane_b32 s39, v255, 22
	v_readlane_b32 s40, v255, 23
	v_readlane_b32 s41, v255, 24
	v_readlane_b32 s42, v255, 25
	v_readlane_b32 s43, v255, 26
	v_readlane_b32 s29, v255, 34
	v_readlane_b32 s31, v255, 36
	v_readlane_b32 s34, v255, 43
	v_readlane_b32 s35, v255, 46
	v_readlane_b32 s13, v255, 49
	s_cmp_lg_u32 s77, 2
	s_cbranch_scc1 .LBB0_666
	v_readlane_b32 s92, v255, 31
	v_readlane_b32 s4, v255, 18
	s_cmpk_lg_i32 s92, 0x100
	s_cbranch_scc1 .LBB0_666
	s_cmpk_lt_u32 s4, 0xb0
	s_cbranch_scc1 .LBB0_666
	v_readlane_b32 s8, v255, 49
	s_lshl_b32 s4, s4, 3
	s_add_i32 s100, s4, s8
	s_addk_i32 s100, 0xfa80
	s_movk_i32 s101, 0x280
	s_branch .Ltail_go

; DI void p0_prologue(const Args& a, LAS unsigned char* lds, int tid, int wave, int lane, bool first) {
;     ...
;     for (int it = gw; it < NITEMS; it += NGW) {
;         int r = it;
;         if (r < 2 * I_UP) { const int which = r >= I_UP; r -= which * I_UP; const int nb = r % (NUP / 32), kb = r / (NUP / 32);
;             p0_transpose_item(a.in[which ? 18 : 12], D, NUP, srccol_up(32 * nb), (bf16_t*)(ws + (which ? WS_WUP2 : WS_WUP1)), 32 * nb, 64 * kb, scr, lane); continue; }
;         r -= 2 * I_UP;
;         if (r < 2 * I_DN) { const int which = r >= I_DN; r -= which * I_DN; const int nb = r % (D / 32), kb = r / (D / 32);
;             p0_transpose_item(a.in[which ? 19 : 13], FF, D, 32 * nb, (bf16_t*)(ws + (which ? WS_WDN2 : WS_WDN1)), 32 * nb, 64 * kb, scr, lane); continue; }
.Ltr_map:
	s_cmpk_lg_i32 s92, 0x100
	s_cbranch_scc1 .Ltr_map_any
	s_cmp_lg_u32 s77, 0
	s_cbranch_scc1 .Ltr_map_tail
	s_cmpk_gt_i32 s100, 0xaff
	s_cbranch_scc1 .LBB0_744
	s_mov_b32 s10, s100
	s_branch .LBB0_720
.Ltr_map_tail:
	s_cmp_lg_u32 s77, 2
	s_cbranch_scc1 .Ltr_map_tail3
	s_cmpk_gt_i32 s100, 0x57f
	s_cbranch_scc1 .LBB0_744
	s_add_i32 s10, s100, 0x1600
	s_branch .LBB0_720
